# attention: row sums of P accumulated in f32 on the VALU (packed adds) instead of 4 ones-MFMAs per tile; rest as previous version
# baseline (speedup 1.0000x reference)
; #define SBAR() __builtin_amdgcn_sched_barrier(0)
; #define RESC(a) do { if (__any((a) < 1.f)) { if (hi == 0) al_l[r32] = (a); asm volatile("s_waitcnt lgkmcnt(0)" ::: "memory"); \
;     _Pragma("unroll") for (int r = 0; r < 16; ++r) { const float f_ = al_l[crow(r, hi)]; o[0][r] *= f_; o[1][r] *= f_; osum[r] *= f_; } } } while (0)
; __device__ __forceinline__ void attn_unit(const bf16_t* __restrict__ Qb, const bf16_t* __restrict__ KNh, const bf16_t* __restrict__ KRb, const bf16_t* __restrict__ Vh, ...
;     ...
;   RESC(alB);
;   finishSM(pB0, pB1, pa0, pa1, pa2, pa3); SBAR();
;   pv_d0(o, osum, vb0 + o_cur, pa0, pa1, pa2, pa3);
;   float rli[16];
; #pragma unroll
;   for (int r = 0; r < 16; ++r) rli[r] = __builtin_amdgcn_rcpf(osum[r]);
.LBB0_703:
	s_or_b64 exec, exec, s[6:7]
	s_waitcnt lgkmcnt(0)
	v_add_u32_e32 v92, s29, v176
	ds_read_b128 v[80:83], v92 offset:224
	ds_read_b128 v[84:87], v92 offset:192
	ds_read_b128 v[88:91], v92 offset:160
	ds_read_b128 v[92:95], v92 offset:128
	s_waitcnt lgkmcnt(3)
	v_pk_mul_f32 v[28:29], v[28:29], v[80:81]
	s_waitcnt lgkmcnt(2)
	v_pk_mul_f32 v[24:25], v[24:25], v[84:85]
	s_waitcnt lgkmcnt(1)
	v_pk_mul_f32 v[20:21], v[20:21], v[88:89]
	v_pk_mul_f32 v[30:31], v[30:31], v[82:83]
	v_pk_mul_f32 v[26:27], v[26:27], v[86:87]
	v_pk_mul_f32 v[22:23], v[22:23], v[90:91]
	s_waitcnt lgkmcnt(0)
	v_pk_mul_f32 v[18:19], v[18:19], v[94:95]
	v_pk_mul_f32 v[16:17], v[16:17], v[92:93]
	v_pk_mul_f32 v[44:45], v[44:45], v[80:81]
	v_pk_mul_f32 v[40:41], v[40:41], v[84:85]
	v_pk_mul_f32 v[36:37], v[36:37], v[88:89]
	v_pk_mul_f32 v[46:47], v[46:47], v[82:83]
	v_pk_mul_f32 v[42:43], v[42:43], v[86:87]
	v_pk_mul_f32 v[38:39], v[38:39], v[90:91]
	v_pk_mul_f32 v[34:35], v[34:35], v[94:95]
	v_pk_mul_f32 v[32:33], v[32:33], v[92:93]
	v_pk_mul_f32 v[48:49], v[48:49], v[112:113] op_sel_hi:[1,0]
.LBB0_704:
	s_lshl_b64 s[6:7], s[30:31], 11
	s_add_u32 s6, s62, s6
	s_addc_u32 s7, s63, s7
	s_lshl_b32 s8, s10, 1
	v_exp_f32_e32 v79, v79
	s_add_u32 s8, s6, s8
	v_exp_f32_e32 v80, v111
	v_exp_f32_e32 v81, v110
	v_exp_f32_e32 v82, v109
	v_exp_f32_e32 v83, v108
	v_exp_f32_e32 v84, v107
	v_exp_f32_e32 v85, v106
	v_exp_f32_e32 v86, v105
	v_exp_f32_e32 v87, v104
	v_exp_f32_e32 v88, v103
	v_exp_f32_e32 v89, v102
	v_exp_f32_e32 v90, v101
	v_exp_f32_e32 v91, v100
	v_exp_f32_e32 v92, v99
	v_exp_f32_e32 v93, v98
	v_exp_f32_e32 v94, v97
	v_exp_f32_e32 v95, v96
	v_exp_f32_e32 v96, v64
	v_exp_f32_e32 v97, v65
	v_exp_f32_e32 v98, v66
	v_exp_f32_e32 v99, v67
	v_exp_f32_e32 v100, v68
	v_exp_f32_e32 v101, v69
	v_exp_f32_e32 v102, v70
	v_exp_f32_e32 v103, v71
	v_exp_f32_e32 v104, v72
	v_exp_f32_e32 v105, v73
	v_exp_f32_e32 v106, v74
	v_exp_f32_e32 v107, v75
	v_exp_f32_e32 v108, v76
	v_exp_f32_e32 v109, v77
	v_exp_f32_e32 v110, v78
	v_add_f32_e32 v48, v48, v95
	v_add_f32_e32 v49, v49, v94
	v_cvt_pk_bf16_f32 v64, v95, v94
	v_add_f32_e32 v48, v48, v93
	v_add_f32_e32 v49, v49, v92
	v_cvt_pk_bf16_f32 v65, v93, v92
	v_add_f32_e32 v48, v48, v91
	v_add_f32_e32 v49, v49, v90
	v_cvt_pk_bf16_f32 v66, v91, v90
	v_add_f32_e32 v48, v48, v89
	v_add_f32_e32 v49, v49, v88
	v_cvt_pk_bf16_f32 v67, v89, v88
	v_add_f32_e32 v48, v48, v87
	v_add_f32_e32 v49, v49, v86
	v_cvt_pk_bf16_f32 v68, v87, v86
	v_add_f32_e32 v48, v48, v85
	v_add_f32_e32 v49, v49, v84
	v_cvt_pk_bf16_f32 v69, v85, v84
	v_add_f32_e32 v48, v48, v83
	v_add_f32_e32 v49, v49, v82
	v_cvt_pk_bf16_f32 v70, v83, v82
	v_add_f32_e32 v48, v48, v81
	v_add_f32_e32 v49, v49, v80
	v_cvt_pk_bf16_f32 v71, v81, v80
	v_add_f32_e32 v48, v48, v96
	v_add_f32_e32 v49, v49, v97
	v_cvt_pk_bf16_f32 v72, v96, v97
	v_add_f32_e32 v48, v48, v98
	v_add_f32_e32 v49, v49, v99
	v_cvt_pk_bf16_f32 v73, v98, v99
	v_add_f32_e32 v48, v48, v100
	v_add_f32_e32 v49, v49, v101
	v_cvt_pk_bf16_f32 v74, v100, v101
	v_add_f32_e32 v48, v48, v102
	v_add_f32_e32 v49, v49, v103
	v_cvt_pk_bf16_f32 v75, v102, v103
	v_add_f32_e32 v48, v48, v104
	v_add_f32_e32 v49, v49, v105
	v_cvt_pk_bf16_f32 v76, v104, v105
	v_add_f32_e32 v48, v48, v106
	v_add_f32_e32 v49, v49, v107
	v_cvt_pk_bf16_f32 v77, v106, v107
	v_add_f32_e32 v48, v48, v108
	v_add_f32_e32 v49, v49, v109
	v_cvt_pk_bf16_f32 v78, v108, v109
	v_add_f32_e32 v48, v48, v110
	v_add_f32_e32 v49, v49, v79
	v_cvt_pk_bf16_f32 v79, v110, v79
	s_addc_u32 s9, s7, 0
	v_permlane32_swap_b32_e32 v64, v66
	v_permlane32_swap_b32_e32 v65, v67
	v_permlane32_swap_b32_e32 v68, v70
	v_permlane32_swap_b32_e32 v69, v71
	v_permlane32_swap_b32_e32 v72, v74
	v_permlane32_swap_b32_e32 v73, v75
	v_permlane32_swap_b32_e32 v76, v78
	v_permlane32_swap_b32_e32 v77, v79
	ds_read_b64_tr_b16 v[80:81], v193 offset:0
	ds_read_b64_tr_b16 v[82:83], v193 offset:0x800
	ds_read_b64_tr_b16 v[84:85], v193 offset:0x1000
	ds_read_b64_tr_b16 v[86:87], v193 offset:0x1800
	ds_read_b64_tr_b16 v[88:89], v193 offset:0x2000
	ds_read_b64_tr_b16 v[90:91], v193 offset:0x2800
	ds_read_b64_tr_b16 v[92:93], v193 offset:0x3000
	ds_read_b64_tr_b16 v[94:95], v193 offset:0x3800
	s_waitcnt lgkmcnt(0)
	s_nop 0
	v_mfma_f32_32x32x16_bf16 v[16:31], v[64:67], v[80:83], v[16:31]
	ds_read_b64_tr_b16 v[80:81], v193 offset:0x200
	ds_read_b64_tr_b16 v[82:83], v193 offset:0xa00
	v_mfma_f32_32x32x16_bf16 v[16:31], v[68:71], v[84:87], v[16:31]
	ds_read_b64_tr_b16 v[84:85], v193 offset:0x1200
	ds_read_b64_tr_b16 v[86:87], v193 offset:0x1a00
	v_mfma_f32_32x32x16_bf16 v[16:31], v[72:75], v[88:91], v[16:31]
	ds_read_b64_tr_b16 v[88:89], v193 offset:0x2200
	ds_read_b64_tr_b16 v[90:91], v193 offset:0x2a00
	ds_read_b64_tr_b16 v[96:97], v193 offset:0x3200
	ds_read_b64_tr_b16 v[98:99], v193 offset:0x3a00
	s_waitcnt lgkmcnt(0)
	v_mfma_f32_32x32x16_bf16 v[16:31], v[76:79], v[92:95], v[16:31]
	v_mfma_f32_32x32x16_bf16 v[32:47], v[64:67], v[80:83], v[32:47]
	s_ashr_i32 s29, s28, 31
	s_lshl_b64 s[6:7], s[28:29], 11
	s_add_u32 s6, s8, s6
	s_addc_u32 s7, s9, s7
	v_lshlrev_b32_e32 v176, 1, v189
	s_add_i32 s76, s76, 1
	s_cmp_eq_u32 s76, 12
	v_mfma_f32_32x32x16_bf16 v[32:47], v[68:71], v[84:87], v[32:47]
	v_mfma_f32_32x32x16_bf16 v[32:47], v[72:75], v[88:91], v[32:47]
	v_mfma_f32_32x32x16_bf16 v[32:47], v[76:79], v[96:99], v[32:47]
	v_add_f32_e32 v48, v48, v49
	v_lshlrev_b32_e32 v80, 2, v189
	v_mov_b32_e32 v49, v48
	v_sub_u32_e32 v80, v192, v80
	v_lshl_add_u32 v80, v190, 4, v80
	s_nop 0
	v_permlane32_swap_b32_e32 v48, v49
	v_add_f32_e32 v48, v48, v49
	ds_write_b32 v192, v48 offset:128
	s_waitcnt lgkmcnt(0)
; __device__ __forceinline__ int crow(int r, int hi) { return (r & 3) + 8 * (r >> 2) + 4 * hi; }
; __device__ __forceinline__ unsigned cvtpk(float lo, float hi) { unsigned r; asm volatile("v_cvt_pk_bf16_f32 %0, %1, %2" : "=v"(r) : "v"(lo), "v"(hi)); return r; }
; __device__ __forceinline__ int crow(int r, int hi) { return (r & 3) + 8 * (r >> 2) + 4 * hi; }
; __device__ __forceinline__ unsigned cvtpk(float lo, float hi) { unsigned r; asm volatile("v_cvt_pk_bf16_f32 %0, %1, %2" : "=v"(r) : "v"(lo), "v"(hi)); return r; }
; __device__ __forceinline__ void attn_unit(const bf16_t* __restrict__ Qb, const bf16_t* __restrict__ KNh, const bf16_t* __restrict__ KRb, const bf16_t* __restrict__ Vh, ...
;     ...
;   float rli[16];
; #pragma unroll
;   for (int r = 0; r < 16; ++r) rli[r] = __builtin_amdgcn_rcpf(osum[r]);
;   bf16_t* Ow = Ob + (long)(wid * QBLK) * LDO;
; #pragma unroll
;   for (int r = 0; r < 16; ++r) { int orow = crow(r, hi);
; #pragma unroll
;     for (int d0 = 0; d0 < 2; ++d0) { const unsigned w = cvtpk(o[d0][r] * rli[r], 0.f); Ow[(long)orow * LDO + d0 * 32 + r32] = (bf16_t)(w & 0xffffu); } }
;   __syncthreads();
	ds_read_b128 v[52:55], v80 offset:160
	ds_read_b128 v[56:59], v80 offset:192
	ds_read_b128 v[60:63], v80 offset:224
	ds_read_b128 v[48:51], v80 offset:128
	s_waitcnt lgkmcnt(0)
	s_nop 10
	v_rcp_f32_e32 v92, v48
	v_rcp_f32_e32 v93, v49
	v_rcp_f32_e32 v94, v50
	v_rcp_f32_e32 v95, v51
	v_lshlrev_b32_e32 v48, 13, v190
	v_lshl_add_u64 v[50:51], s[6:7], 0, v[176:177]
	v_mov_b32_e32 v49, v177
	v_mul_f32_e32 v16, v16, v92
	v_lshl_add_u64 v[48:49], v[50:51], 0, v[48:49]
	v_cvt_pk_bf16_f32 v16, v16, v177
	global_store_short v[48:49], v16, off
	v_mul_f32_e32 v16, v32, v92
	v_cvt_pk_bf16_f32 v16, v16, v177
	global_store_short v[48:49], v16, off offset:64
	v_mul_f32_e32 v16, v17, v93
	v_cvt_pk_bf16_f32 v16, v16, v177
	global_store_short v[48:49], v16, off offset:2048
	v_mul_f32_e32 v16, v33, v93
	v_cvt_pk_bf16_f32 v16, v16, v177
	global_store_short v[48:49], v16, off offset:2112
	v_mul_f32_e32 v16, v18, v94
	v_cvt_pk_bf16_f32 v18, v16, v177
	v_add_co_u32_e32 v16, vcc, s48, v48
	v_rcp_f32_e32 v52, v52
	s_nop 0
	v_addc_co_u32_e32 v17, vcc, 0, v49, vcc
	global_store_short v[16:17], v18, off
	v_mul_f32_e32 v18, v34, v94
	v_cvt_pk_bf16_f32 v18, v18, v177
	global_store_short v[16:17], v18, off offset:64
	v_mul_f32_e32 v18, v19, v95
	v_cvt_pk_bf16_f32 v18, v18, v177
	global_store_short v[16:17], v18, off offset:2048
	v_mul_f32_e32 v18, v35, v95
	v_cvt_pk_bf16_f32 v18, v18, v177
	global_store_short v[16:17], v18, off offset:2112
	v_mul_f32_e32 v16, v20, v52
	v_cvt_pk_bf16_f32 v20, v16, v177
	v_add_co_u32_e32 v16, vcc, s45, v48
	v_rcp_f32_e32 v53, v53
	s_nop 0
	v_addc_co_u32_e32 v17, vcc, 0, v49, vcc
	v_add_co_u32_e32 v18, vcc, s72, v48
	v_rcp_f32_e32 v54, v54
	s_nop 0
	v_addc_co_u32_e32 v19, vcc, 0, v49, vcc
	global_store_short v[18:19], v20, off offset:-4096
	v_mul_f32_e32 v20, v36, v52
	v_cvt_pk_bf16_f32 v20, v20, v177
	global_store_short v[16:17], v20, off offset:64
	v_mul_f32_e32 v20, v21, v53
	v_cvt_pk_bf16_f32 v20, v20, v177
	global_store_short v[16:17], v20, off offset:2048
	v_mul_f32_e32 v20, v37, v53
	v_rcp_f32_e32 v55, v55
	v_cvt_pk_bf16_f32 v20, v20, v177
	global_store_short v[16:17], v20, off offset:2112
	v_mul_f32_e32 v16, v22, v54
	v_cvt_pk_bf16_f32 v16, v16, v177
	global_store_short v[18:19], v16, off
	v_mul_f32_e32 v16, v38, v54
	v_cvt_pk_bf16_f32 v16, v16, v177
	v_rcp_f32_e32 v56, v56
	global_store_short v[18:19], v16, off offset:64
	v_mul_f32_e32 v16, v23, v55
	v_cvt_pk_bf16_f32 v16, v16, v177
	global_store_short v[18:19], v16, off offset:2048
	v_mul_f32_e32 v16, v39, v55
	v_cvt_pk_bf16_f32 v16, v16, v177
	global_store_short v[18:19], v16, off offset:2112
	v_mul_f32_e32 v16, v24, v56
	v_cvt_pk_bf16_f32 v20, v16, v177
	v_add_co_u32_e32 v16, vcc, s47, v48
	v_rcp_f32_e32 v57, v57
	s_nop 0
	v_addc_co_u32_e32 v17, vcc, 0, v49, vcc
	v_add_co_u32_e32 v18, vcc, s73, v48
	v_rcp_f32_e32 v58, v58
	s_nop 0
	v_addc_co_u32_e32 v19, vcc, 0, v49, vcc
	global_store_short v[18:19], v20, off offset:-4096
	v_mul_f32_e32 v20, v40, v56
	v_cvt_pk_bf16_f32 v20, v20, v177
	global_store_short v[16:17], v20, off offset:64
	v_mul_f32_e32 v20, v25, v57
	v_cvt_pk_bf16_f32 v20, v20, v177
	global_store_short v[16:17], v20, off offset:2048
	v_mul_f32_e32 v20, v41, v57
	v_rcp_f32_e32 v59, v59
	v_cvt_pk_bf16_f32 v20, v20, v177
	global_store_short v[16:17], v20, off offset:2112
	v_mul_f32_e32 v16, v26, v58
	v_cvt_pk_bf16_f32 v16, v16, v177
	global_store_short v[18:19], v16, off
	v_mul_f32_e32 v16, v42, v58
	v_cvt_pk_bf16_f32 v16, v16, v177
	v_rcp_f32_e32 v60, v60
	global_store_short v[18:19], v16, off offset:64
	v_mul_f32_e32 v16, v27, v59
	v_cvt_pk_bf16_f32 v16, v16, v177
	global_store_short v[18:19], v16, off offset:2048
	v_mul_f32_e32 v16, v43, v59
	v_cvt_pk_bf16_f32 v16, v16, v177
	global_store_short v[18:19], v16, off offset:2112
	v_mul_f32_e32 v16, v28, v60
	v_cvt_pk_bf16_f32 v20, v16, v177
	v_add_co_u32_e32 v16, vcc, s74, v48
	v_rcp_f32_e32 v61, v61
	s_nop 0
	v_addc_co_u32_e32 v17, vcc, 0, v49, vcc
	v_add_co_u32_e32 v18, vcc, s75, v48
	v_rcp_f32_e32 v62, v62
	s_nop 0
	v_addc_co_u32_e32 v19, vcc, 0, v49, vcc
	global_store_short v[18:19], v20, off offset:-4096
	v_mul_f32_e32 v20, v44, v60
	v_cvt_pk_bf16_f32 v20, v20, v177
	global_store_short v[16:17], v20, off offset:64
	v_mul_f32_e32 v20, v29, v61
	v_cvt_pk_bf16_f32 v20, v20, v177
	global_store_short v[16:17], v20, off offset:2048
	v_mul_f32_e32 v20, v45, v61
	v_rcp_f32_e32 v63, v63
	v_cvt_pk_bf16_f32 v20, v20, v177
	global_store_short v[16:17], v20, off offset:2112
	v_mul_f32_e32 v16, v30, v62
	v_cvt_pk_bf16_f32 v16, v16, v177
	global_store_short v[18:19], v16, off
	v_mul_f32_e32 v16, v46, v62
	v_cvt_pk_bf16_f32 v16, v16, v177
	global_store_short v[18:19], v16, off offset:64
	v_mul_f32_e32 v16, v31, v63
	v_cvt_pk_bf16_f32 v16, v16, v177
	global_store_short v[18:19], v16, off offset:2048
	v_mul_f32_e32 v16, v47, v63
	v_cvt_pk_bf16_f32 v16, v16, v177
	global_store_short v[18:19], v16, off offset:2112
	s_barrier
	s_cbranch_scc1 .LBB0_760

; #define SBAR() __builtin_amdgcn_sched_barrier(0)
; #define SLOAD(i, k0) do { sr_[i].v = *reinterpret_cast<const bf16x8*>(vp + (long)(k0) * LDV); sr_[i].k = *reinterpret_cast<const bf16x8*>(kp + (long)(k0) * LDKN); \
;     if (has_r) sr_[i].r = *reinterpret_cast<const bf16x8*>(rp + (long)(k0) * LDKR); } while (0)
; __device__ __forceinline__ void finishSM(f32x16& p0, f32x16& p1, bf16x8& pa0, bf16x8& pa1, bf16x8& pa2, bf16x8& pa3) {
; #pragma unroll
;   for (int r = 0; r < 16; ++r) p1[r] = __builtin_amdgcn_exp2f(p1[r]);
;     ...
;   PK4(p0, 0, pa0); PK4(p0, 8, pa1); PK4(p1, 0, pa2); PK4(p1, 8, pa3);
; __device__ __forceinline__ void attn_unit(const bf16_t* __restrict__ Qb, const bf16_t* __restrict__ KNh, const bf16_t* __restrict__ KRb, const bf16_t* __restrict__ Vh, ...
;     ...
;     SBAR(); qkt(pB0, pB1, (bf16_t*)((char*)K_lds + o_cur), qr, negm, r32, hi);
;     finishSM(pA0, pA1, pa0, pa1, pa2, pa3); SBAR();
;     SLOAD(SO, (j + 2) * KVBLK); SBAR();
;     pv_d0(o, osum, vb0 + o_prev, pa0, pa1, pa2, pa3); partialSM<false>(pB0, pB1, m_ref, negm, alB);
.Lattn_h1_norope:
	v_exp_f32_e32 v87, v87
	v_exp_f32_e32 v88, v88
	v_exp_f32_e32 v89, v89
	v_exp_f32_e32 v90, v90
	v_exp_f32_e32 v91, v91
	v_exp_f32_e32 v238, v81
	v_pk_add_f32 v[48:49], v[48:49], v[88:89]
	v_pk_add_f32 v[48:49], v[48:49], v[90:91]
	v_add_f32_e32 v48, v48, v87
	v_pk_add_f32 v[48:49], v[48:49], v[0:1]
	v_pk_add_f32 v[48:49], v[48:49], v[2:3]
	s_waitcnt lgkmcnt(1)
	v_mfma_f32_32x32x16_bf16 v[112:127], v[96:99], v[156:159], v[64:79]
	v_exp_f32_e32 v239, v82
	v_exp_f32_e32 v240, v83
	v_exp_f32_e32 v241, v84
	v_pk_add_f32 v[48:49], v[48:49], v[238:239]
	v_pk_add_f32 v[48:49], v[48:49], v[4:5]
	v_pk_add_f32 v[48:49], v[48:49], v[6:7]
	s_waitcnt lgkmcnt(0)
	v_mfma_f32_32x32x16_bf16 v[96:111], v[210:213], v[156:159], v[64:79]
	v_pk_add_f32 v[48:49], v[48:49], v[240:241]
	v_pk_add_f32 v[48:49], v[48:49], v[8:9]
	v_pk_add_f32 v[48:49], v[48:49], v[10:11]
	v_pk_add_f32 v[48:49], v[48:49], v[12:13]
	v_pk_add_f32 v[48:49], v[48:49], v[14:15]
	ds_read_b128 v[210:213], v193 offset:49152
	s_waitcnt lgkmcnt(0)
	v_mfma_f32_32x32x16_bf16 v[112:127], v[210:213], v[152:155], v[112:127]
	ds_read_b128 v[210:213], v193 offset:57344
	v_add_u32_e32 v193, s36, v199
	ds_read_b128 v[214:217], v193 offset:57344
	ds_read_b128 v[218:221], v193 offset:49152
	v_add_u32_e32 v193, s36, v200
	s_waitcnt lgkmcnt(2)
	v_mfma_f32_32x32x16_bf16 v[96:111], v[210:213], v[152:155], v[96:111]
	ds_read_b128 v[210:213], v193 offset:57344
	ds_read_b128 v[222:225], v193 offset:49152
	v_add_u32_e32 v193, s36, v201
	ds_read_b128 v[226:229], v193 offset:57344
	ds_read_b128 v[230:233], v193 offset:49152
	v_add_u32_e32 v193, s36, v202
	s_waitcnt lgkmcnt(4)
	v_mfma_f32_32x32x16_bf16 v[112:127], v[218:221], v[148:151], v[112:127]
	ds_read_b128 v[218:221], v193 offset:57344
	ds_read_b128 v[234:237], v193 offset:49152
	v_exp_f32_e32 v193, v80
	v_mfma_f32_32x32x16_bf16 v[96:111], v[214:217], v[148:151], v[96:111]
	v_exp_f32_e32 v214, v85
	v_exp_f32_e32 v215, v86
	v_exp_f32_e32 v216, v92
	v_exp_f32_e32 v217, v93
	v_cvt_pk_bf16_f32 v92, v0, v1
	v_cvt_pk_bf16_f32 v93, v2, v3
	v_add_f32_e32 v49, v49, v193
	v_pk_add_f32 v[48:49], v[48:49], v[214:215]
	v_pk_add_f32 v[48:49], v[48:49], v[216:217]
	s_waitcnt lgkmcnt(4)
	v_mfma_f32_32x32x16_bf16 v[112:127], v[222:225], v[136:139], v[112:127]
	v_exp_f32_e32 v222, v94
	v_exp_f32_e32 v223, v95
	v_cvt_pk_bf16_f32 v94, v4, v5
	v_cvt_pk_bf16_f32 v95, v6, v7
	v_pk_add_f32 v[48:49], v[48:49], v[222:223]
	v_cvt_pk_bf16_f32 v80, v8, v9
	v_cvt_pk_bf16_f32 v81, v10, v11
	v_cvt_pk_bf16_f32 v82, v12, v13
	v_mfma_f32_32x32x16_bf16 v[96:111], v[210:213], v[136:139], v[96:111]
	v_cvt_pk_bf16_f32 v83, v14, v15
	v_cvt_pk_bf16_f32 v84, v193, v238
	v_cvt_pk_bf16_f32 v85, v239, v240
	v_cvt_pk_bf16_f32 v86, v241, v214
	v_cvt_pk_bf16_f32 v87, v215, v87
	v_cvt_pk_bf16_f32 v88, v88, v89
	v_cvt_pk_bf16_f32 v89, v90, v91
	s_waitcnt lgkmcnt(2)
	v_mfma_f32_32x32x16_bf16 v[112:127], v[230:233], v[140:143], v[112:127]
	v_cvt_pk_bf16_f32 v90, v216, v217
	v_cvt_pk_bf16_f32 v91, v222, v223
	v_permlane32_swap_b32_e32 v92, v94
	v_permlane32_swap_b32_e32 v93, v95
	v_permlane32_swap_b32_e32 v80, v82
	v_mfma_f32_32x32x16_bf16 v[96:111], v[226:229], v[140:143], v[96:111]
	v_permlane32_swap_b32_e32 v81, v83
	v_permlane32_swap_b32_e32 v84, v86
	v_permlane32_swap_b32_e32 v85, v87
	v_permlane32_swap_b32_e32 v88, v90
	s_waitcnt lgkmcnt(0)
	v_mfma_f32_32x32x16_bf16 v[112:127], v[234:237], v[128:131], v[112:127]
	v_permlane32_swap_b32_e32 v89, v91
	v_mfma_f32_32x32x16_bf16 v[96:111], v[218:221], v[128:131], v[96:111]
.LBB0_724:
	v_add_u32_e32 v193, s77, v203
	ds_read_b64_tr_b16 v[204:205], v193 offset:0
	ds_read_b64_tr_b16 v[206:207], v193 offset:0x800
	ds_read_b64_tr_b16 v[208:209], v193 offset:0x1000
	ds_read_b64_tr_b16 v[210:211], v193 offset:0x1800
	ds_read_b64_tr_b16 v[212:213], v193 offset:0x2000
	ds_read_b64_tr_b16 v[214:215], v193 offset:0x2800
	ds_read_b64_tr_b16 v[216:217], v193 offset:0x3000
	ds_read_b64_tr_b16 v[218:219], v193 offset:0x3800
	s_waitcnt lgkmcnt(0)
	s_nop 0
	v_mfma_f32_32x32x16_bf16 v[16:31], v[92:95], v[204:207], v[16:31]
	ds_read_b64_tr_b16 v[204:205], v193 offset:0x200
	ds_read_b64_tr_b16 v[206:207], v193 offset:0xa00
	v_max_f32_e32 v254, v113, v113
	v_max_f32_e32 v255, v112, v112
	v_max_f32_e32 v254, v255, v254
	v_max3_f32 v254, v254, v114, v115
	v_max3_f32 v254, v254, v116, v117
	v_mfma_f32_32x32x16_bf16 v[16:31], v[80:83], v[208:211], v[16:31]
	ds_read_b64_tr_b16 v[208:209], v193 offset:0x1200
	ds_read_b64_tr_b16 v[210:211], v193 offset:0x1a00
	v_max3_f32 v254, v254, v118, v119
	v_max3_f32 v254, v254, v120, v121
	v_max3_f32 v254, v254, v122, v123
	v_max3_f32 v254, v254, v124, v125
	v_max3_f32 v254, v254, v126, v127
	v_mfma_f32_32x32x16_bf16 v[16:31], v[84:87], v[212:215], v[16:31]
	ds_read_b64_tr_b16 v[212:213], v193 offset:0x2200
	ds_read_b64_tr_b16 v[214:215], v193 offset:0x2a00
	ds_read_b64_tr_b16 v[220:221], v193 offset:0x3200
	ds_read_b64_tr_b16 v[222:223], v193 offset:0x3a00
	v_max3_f32 v254, v254, v96, v97
	v_max3_f32 v254, v254, v98, v99
	v_max3_f32 v254, v254, v100, v101
	v_max3_f32 v254, v254, v102, v103
	v_max3_f32 v254, v254, v104, v105
	s_waitcnt lgkmcnt(0)
	v_mfma_f32_32x32x16_bf16 v[16:31], v[88:91], v[216:219], v[16:31]
	v_max3_f32 v254, v254, v106, v107
	v_max3_f32 v254, v254, v108, v109
	v_max3_f32 v254, v254, v110, v111
	v_mov_b32_e32 v255, v254
	v_mfma_f32_32x32x16_bf16 v[32:47], v[92:95], v[204:207], v[32:47]
	s_nop 0
	v_permlane32_swap_b32_e32 v254, v255
	v_max_f32_e32 v255, v255, v255
	v_max_f32_e32 v254, v254, v254
	v_max_f32_e32 v255, v254, v255
	v_cmp_ge_f32_e32 vcc, s71, v255
	s_cmp_eq_u64 vcc, exec
	v_mov_b32_e32 v254, 1.0
	s_cbranch_scc0 .Lattn_adj_h1
.Lattn_cont_h1:
	v_mfma_f32_32x32x16_bf16 v[32:47], v[80:83], v[208:211], v[32:47]
	v_exp_f32_e32 v232, v112
	v_exp_f32_e32 v233, v113
	v_exp_f32_e32 v234, v114
	v_exp_f32_e32 v235, v115
	v_exp_f32_e32 v236, v116
	v_mfma_f32_32x32x16_bf16 v[32:47], v[84:87], v[212:215], v[32:47]
	v_exp_f32_e32 v237, v117
	v_exp_f32_e32 v238, v118
	v_exp_f32_e32 v239, v119
	v_exp_f32_e32 v240, v120
	v_exp_f32_e32 v241, v121
	v_mfma_f32_32x32x16_bf16 v[32:47], v[88:91], v[220:223], v[32:47]
	v_exp_f32_e32 v242, v122
	v_exp_f32_e32 v243, v123
	v_exp_f32_e32 v244, v124
	v_exp_f32_e32 v245, v125
	v_exp_f32_e32 v246, v126
	v_exp_f32_e32 v247, v127
	s_mov_b64 s[36:37], -1
	s_and_b64 vcc, exec, s[34:35]
	s_cbranch_vccz .LBB0_728

.LBB0_732:
	v_cmp_gt_f32_e32 vcc, 1.0, v254
	s_cbranch_vccz .LBB0_736
	s_and_saveexec_b64 s[36:37], s[8:9]
	ds_write_b32 v192, v254 offset:128
	s_or_b64 exec, exec, s[36:37]
	s_waitcnt lgkmcnt(0)
	v_add_u32_e32 v92, s29, v176
	ds_read_b128 v[80:83], v92 offset:224
	ds_read_b128 v[84:87], v92 offset:192
	ds_read_b128 v[88:91], v92 offset:160
	ds_read_b128 v[92:95], v92 offset:128
	s_waitcnt lgkmcnt(3)
	v_pk_mul_f32 v[28:29], v[28:29], v[80:81]
	s_waitcnt lgkmcnt(2)
	v_pk_mul_f32 v[24:25], v[24:25], v[84:85]
	s_waitcnt lgkmcnt(1)
	v_pk_mul_f32 v[20:21], v[20:21], v[88:89]
	v_pk_mul_f32 v[30:31], v[30:31], v[82:83]
	v_pk_mul_f32 v[26:27], v[26:27], v[86:87]
	v_pk_mul_f32 v[22:23], v[22:23], v[90:91]
	s_waitcnt lgkmcnt(0)
	v_pk_mul_f32 v[18:19], v[18:19], v[94:95]
	v_pk_mul_f32 v[16:17], v[16:17], v[92:93]
	v_pk_mul_f32 v[44:45], v[44:45], v[80:81]
	v_pk_mul_f32 v[40:41], v[40:41], v[84:85]
	v_pk_mul_f32 v[36:37], v[36:37], v[88:89]
	v_pk_mul_f32 v[46:47], v[46:47], v[82:83]
	v_pk_mul_f32 v[42:43], v[42:43], v[86:87]
	v_pk_mul_f32 v[38:39], v[38:39], v[90:91]
	v_pk_mul_f32 v[34:35], v[34:35], v[94:95]
	v_pk_mul_f32 v[32:33], v[32:33], v[92:93]
	v_pk_mul_f32 v[48:49], v[48:49], v[254:255] op_sel_hi:[1,0]

; #define SBAR() __builtin_amdgcn_sched_barrier(0)
; #define SLOAD(i, k0) do { sr_[i].v = *reinterpret_cast<const bf16x8*>(vp + (long)(k0) * LDV); sr_[i].k = *reinterpret_cast<const bf16x8*>(kp + (long)(k0) * LDKN); \
;     if (has_r) sr_[i].r = *reinterpret_cast<const bf16x8*>(rp + (long)(k0) * LDKR); } while (0)
; __device__ __forceinline__ void finishSM(f32x16& p0, f32x16& p1, bf16x8& pa0, bf16x8& pa1, bf16x8& pa2, bf16x8& pa3) {
; #pragma unroll
;   for (int r = 0; r < 16; ++r) p1[r] = __builtin_amdgcn_exp2f(p1[r]);
;     ...
;   PK4(p0, 0, pa0); PK4(p0, 8, pa1); PK4(p1, 0, pa2); PK4(p1, 8, pa3);
; __device__ __forceinline__ void attn_unit(const bf16_t* __restrict__ Qb, const bf16_t* __restrict__ KNh, const bf16_t* __restrict__ KRb, const bf16_t* __restrict__ Vh, ...
;     ...
;     SBAR(); qkt(pA0, pA1, (bf16_t*)((char*)K_lds + o_cur), qr, negm, r32, hi);
;     finishSM(pB0, pB1, pa0, pa1, pa2, pa3); SBAR();
;     if (j + 3 < NT) SLOAD(SE, (j + 3) * KVBLK); SBAR();
;     pv_d0(o, osum, vb0 + o_prev, pa0, pa1, pa2, pa3); partialSM<false>(pA0, pA1, m_ref, negm, alA);
.Lattn_h2_noload:
	v_exp_f32_e32 v103, v103
	v_exp_f32_e32 v104, v104
	s_waitcnt lgkmcnt(1)
	v_mfma_f32_32x32x16_bf16 v[112:127], v[80:83], v[156:159], v[64:79]
	v_exp_f32_e32 v105, v105
	v_exp_f32_e32 v106, v106
	v_exp_f32_e32 v107, v107
	v_pk_add_f32 v[48:49], v[48:49], v[104:105]
	v_add_f32_e32 v48, v48, v103
	v_pk_add_f32 v[48:49], v[48:49], v[232:233]
	v_pk_add_f32 v[48:49], v[48:49], v[234:235]
	v_exp_f32_e32 v248, v96
	v_exp_f32_e32 v249, v97
	v_pk_add_f32 v[48:49], v[48:49], v[106:107]
	v_exp_f32_e32 v250, v98
	v_exp_f32_e32 v251, v99
	s_waitcnt lgkmcnt(0)
	v_mfma_f32_32x32x16_bf16 v[80:95], v[204:207], v[156:159], v[64:79]
	v_pk_add_f32 v[48:49], v[48:49], v[248:249]
	v_pk_add_f32 v[48:49], v[48:49], v[250:251]
	v_pk_add_f32 v[48:49], v[48:49], v[236:237]
	v_pk_add_f32 v[48:49], v[48:49], v[238:239]
	v_pk_add_f32 v[48:49], v[48:49], v[240:241]
	ds_read_b128 v[204:207], v208 offset:49152
	v_exp_f32_e32 v252, v100
	s_waitcnt lgkmcnt(0)
	v_mfma_f32_32x32x16_bf16 v[112:127], v[204:207], v[152:155], v[112:127]
	v_add_f32_e32 v49, v49, v252
	v_pk_add_f32 v[48:49], v[48:49], v[242:243]
	v_pk_add_f32 v[48:49], v[48:49], v[244:245]
	v_pk_add_f32 v[48:49], v[48:49], v[246:247]
	ds_read_b128 v[204:207], v208 offset:57344
	ds_read_b128 v[208:211], v212 offset:57344
	ds_read_b128 v[212:215], v212 offset:49152
	s_waitcnt lgkmcnt(2)
	v_mfma_f32_32x32x16_bf16 v[80:95], v[204:207], v[152:155], v[80:95]
	ds_read_b128 v[204:207], v216 offset:57344
	ds_read_b128 v[216:219], v216 offset:49152
	ds_read_b128 v[220:223], v224 offset:57344
	ds_read_b128 v[224:227], v224 offset:49152
	s_waitcnt lgkmcnt(4)
	v_mfma_f32_32x32x16_bf16 v[112:127], v[212:215], v[148:151], v[112:127]
	ds_read_b128 v[212:215], v228 offset:57344
	ds_read_b128 v[228:231], v228 offset:49152
	v_mfma_f32_32x32x16_bf16 v[80:95], v[208:211], v[148:151], v[80:95]
	v_exp_f32_e32 v208, v101
	v_exp_f32_e32 v209, v102
	v_exp_f32_e32 v210, v108
	v_exp_f32_e32 v211, v109
	v_cvt_pk_bf16_f32 v108, v232, v233
	v_cvt_pk_bf16_f32 v109, v234, v235
	v_pk_add_f32 v[48:49], v[48:49], v[208:209]
	v_pk_add_f32 v[48:49], v[48:49], v[210:211]
	s_waitcnt lgkmcnt(4)
	v_mfma_f32_32x32x16_bf16 v[112:127], v[216:219], v[136:139], v[112:127]
	v_exp_f32_e32 v216, v110
	v_exp_f32_e32 v217, v111
	v_cvt_pk_bf16_f32 v110, v236, v237
	v_pk_add_f32 v[48:49], v[48:49], v[216:217]
	v_cvt_pk_bf16_f32 v111, v238, v239
	v_cvt_pk_bf16_f32 v96, v240, v241
	v_cvt_pk_bf16_f32 v97, v242, v243
	v_cvt_pk_bf16_f32 v98, v244, v245
	v_mfma_f32_32x32x16_bf16 v[80:95], v[204:207], v[136:139], v[80:95]
	v_cvt_pk_bf16_f32 v99, v246, v247
	v_cvt_pk_bf16_f32 v100, v248, v249
	v_cvt_pk_bf16_f32 v101, v250, v251
	v_cvt_pk_bf16_f32 v102, v252, v208
	v_cvt_pk_bf16_f32 v103, v209, v103
	v_cvt_pk_bf16_f32 v104, v104, v105
	v_cvt_pk_bf16_f32 v105, v106, v107
	s_waitcnt lgkmcnt(2)
	v_mfma_f32_32x32x16_bf16 v[112:127], v[224:227], v[140:143], v[112:127]
	v_cvt_pk_bf16_f32 v106, v210, v211
	v_cvt_pk_bf16_f32 v107, v216, v217
	v_permlane32_swap_b32_e32 v108, v110
	v_permlane32_swap_b32_e32 v109, v111
	v_permlane32_swap_b32_e32 v96, v98
	v_mfma_f32_32x32x16_bf16 v[80:95], v[220:223], v[140:143], v[80:95]
	v_permlane32_swap_b32_e32 v97, v99
	v_permlane32_swap_b32_e32 v100, v102
	v_permlane32_swap_b32_e32 v101, v103
	v_permlane32_swap_b32_e32 v104, v106
	s_waitcnt lgkmcnt(0)
	v_mfma_f32_32x32x16_bf16 v[112:127], v[228:231], v[128:131], v[112:127]
	v_permlane32_swap_b32_e32 v105, v107
	v_mfma_f32_32x32x16_bf16 v[80:95], v[212:215], v[128:131], v[80:95]
.LBB0_739:
	v_add_u32_e32 v182, s41, v203
	ds_read_b64_tr_b16 v[204:205], v182 offset:0
	ds_read_b64_tr_b16 v[206:207], v182 offset:0x800
	ds_read_b64_tr_b16 v[208:209], v182 offset:0x1000
	ds_read_b64_tr_b16 v[210:211], v182 offset:0x1800
	ds_read_b64_tr_b16 v[212:213], v182 offset:0x2000
	ds_read_b64_tr_b16 v[214:215], v182 offset:0x2800
	ds_read_b64_tr_b16 v[216:217], v182 offset:0x3000
	ds_read_b64_tr_b16 v[218:219], v182 offset:0x3800
	s_waitcnt lgkmcnt(0)
	s_nop 0
	v_mfma_f32_32x32x16_bf16 v[16:31], v[108:111], v[204:207], v[16:31]
	ds_read_b64_tr_b16 v[204:205], v182 offset:0x200
	ds_read_b64_tr_b16 v[206:207], v182 offset:0xa00
	v_max_f32_e32 v254, v113, v113
	v_max_f32_e32 v255, v112, v112
	v_max_f32_e32 v254, v255, v254
	v_max3_f32 v254, v254, v114, v115
	v_max3_f32 v254, v254, v116, v117
	v_mfma_f32_32x32x16_bf16 v[16:31], v[96:99], v[208:211], v[16:31]
	ds_read_b64_tr_b16 v[208:209], v182 offset:0x1200
	ds_read_b64_tr_b16 v[210:211], v182 offset:0x1a00
	v_max3_f32 v254, v254, v118, v119
	v_max3_f32 v254, v254, v120, v121
	v_max3_f32 v254, v254, v122, v123
	v_max3_f32 v254, v254, v124, v125
	v_max3_f32 v254, v254, v126, v127
	v_mfma_f32_32x32x16_bf16 v[16:31], v[100:103], v[212:215], v[16:31]
	ds_read_b64_tr_b16 v[212:213], v182 offset:0x2200
	ds_read_b64_tr_b16 v[214:215], v182 offset:0x2a00
	ds_read_b64_tr_b16 v[220:221], v182 offset:0x3200
	ds_read_b64_tr_b16 v[222:223], v182 offset:0x3a00
	v_max3_f32 v254, v254, v80, v81
	v_max3_f32 v254, v254, v82, v83
	v_max3_f32 v254, v254, v84, v85
	v_max3_f32 v254, v254, v86, v87
	v_max3_f32 v254, v254, v88, v89
	s_waitcnt lgkmcnt(0)
	v_mfma_f32_32x32x16_bf16 v[16:31], v[104:107], v[216:219], v[16:31]
	v_max3_f32 v254, v254, v90, v91
	v_max3_f32 v254, v254, v92, v93
	v_max3_f32 v254, v254, v94, v95
	v_mov_b32_e32 v255, v254
	v_mfma_f32_32x32x16_bf16 v[32:47], v[108:111], v[204:207], v[32:47]
	s_nop 0
	v_permlane32_swap_b32_e32 v254, v255
	v_max_f32_e32 v255, v255, v255
	v_max_f32_e32 v254, v254, v254
	v_max_f32_e32 v255, v254, v255
	v_cmp_ge_f32_e32 vcc, s71, v255
	s_cmp_eq_u64 vcc, exec
	v_mov_b32_e32 v254, 1.0
	s_cbranch_scc0 .Lattn_adj_h2
.Lattn_cont_h2:
	v_mfma_f32_32x32x16_bf16 v[32:47], v[96:99], v[208:211], v[32:47]
	v_exp_f32_e32 v0, v112
	v_exp_f32_e32 v1, v113
	v_exp_f32_e32 v2, v114
	v_exp_f32_e32 v3, v115
	v_exp_f32_e32 v4, v116
	v_mfma_f32_32x32x16_bf16 v[32:47], v[100:103], v[212:215], v[32:47]
	v_exp_f32_e32 v5, v117
	v_exp_f32_e32 v6, v118
	v_exp_f32_e32 v7, v119
	v_exp_f32_e32 v8, v120
	v_exp_f32_e32 v9, v121
	v_mfma_f32_32x32x16_bf16 v[32:47], v[104:107], v[220:223], v[32:47]
	v_exp_f32_e32 v10, v122
	v_exp_f32_e32 v11, v123
	v_exp_f32_e32 v12, v124
	v_exp_f32_e32 v13, v125
	v_exp_f32_e32 v14, v126
	v_exp_f32_e32 v15, v127
	s_mov_b64 s[38:39], -1
	s_and_b64 vcc, exec, s[34:35]
	s_cbranch_vccz .LBB0_743

.LBB0_747:
	v_cmp_gt_f32_e32 vcc, 1.0, v254
	s_cbranch_vccz .LBB0_751
	s_and_saveexec_b64 s[38:39], s[8:9]
	ds_write_b32 v192, v254 offset:128
	s_or_b64 exec, exec, s[38:39]
	s_waitcnt lgkmcnt(0)
	v_add_u32_e32 v108, s29, v176
	ds_read_b128 v[96:99], v108 offset:224
	ds_read_b128 v[100:103], v108 offset:192
	ds_read_b128 v[104:107], v108 offset:160
	ds_read_b128 v[108:111], v108 offset:128
	s_waitcnt lgkmcnt(3)
	v_pk_mul_f32 v[28:29], v[28:29], v[96:97]
	s_waitcnt lgkmcnt(2)
	v_pk_mul_f32 v[24:25], v[24:25], v[100:101]
	s_waitcnt lgkmcnt(1)
	v_pk_mul_f32 v[20:21], v[20:21], v[104:105]
	v_pk_mul_f32 v[30:31], v[30:31], v[98:99]
	v_pk_mul_f32 v[26:27], v[26:27], v[102:103]
	v_pk_mul_f32 v[22:23], v[22:23], v[106:107]
	s_waitcnt lgkmcnt(0)
	v_pk_mul_f32 v[18:19], v[18:19], v[110:111]
	v_pk_mul_f32 v[16:17], v[16:17], v[108:109]
	v_pk_mul_f32 v[44:45], v[44:45], v[96:97]
	v_pk_mul_f32 v[40:41], v[40:41], v[100:101]
	v_pk_mul_f32 v[36:37], v[36:37], v[104:105]
	v_pk_mul_f32 v[46:47], v[46:47], v[98:99]
	v_pk_mul_f32 v[42:43], v[42:43], v[102:103]
	v_pk_mul_f32 v[38:39], v[38:39], v[106:107]
	v_pk_mul_f32 v[34:35], v[34:35], v[110:111]
	v_pk_mul_f32 v[32:33], v[32:33], v[108:109]
	v_pk_mul_f32 v[48:49], v[48:49], v[254:255] op_sel_hi:[1,0]

; #define SBAR() __builtin_amdgcn_sched_barrier(0)
; __device__ __forceinline__ void finishSM(f32x16& p0, f32x16& p1, bf16x8& pa0, bf16x8& pa1, bf16x8& pa2, bf16x8& pa3) {
; #pragma unroll
;   for (int r = 0; r < 16; ++r) p1[r] = __builtin_amdgcn_exp2f(p1[r]);
;     ...
;   PK4(p0, 0, pa0); PK4(p0, 8, pa1); PK4(p1, 0, pa2); PK4(p1, 8, pa3);
; __device__ __forceinline__ void attn_unit(const bf16_t* __restrict__ Qb, const bf16_t* __restrict__ KNh, const bf16_t* __restrict__ KRb, const bf16_t* __restrict__ Vh, ...
;     ...
;   SBAR(); qkt(pB0, pB1, (bf16_t*)((char*)K_lds + o_cur), qr, negm, r32, hi);
;   finishSM(pA0, pA1, pa0, pa1, pa2, pa3); SBAR();
;   pv_d0(o, osum, vb0 + o_prev, pa0, pa1, pa2, pa3); partialSM<false>(pB0, pB1, m_ref, negm, alB);
.LBB0_755:
	v_exp_f32_e32 v183, v112
	v_exp_f32_e32 v207, v113
	v_exp_f32_e32 v204, v114
	v_exp_f32_e32 v208, v115
	v_exp_f32_e32 v205, v116
	v_exp_f32_e32 v209, v117
	v_exp_f32_e32 v182, v118
	v_exp_f32_e32 v206, v119
	v_exp_f32_e32 v171, v120
	v_exp_f32_e32 v174, v121
	v_exp_f32_e32 v172, v122
	v_exp_f32_e32 v175, v123
	v_exp_f32_e32 v169, v124
	v_exp_f32_e32 v173, v125
	v_exp_f32_e32 v168, v126
	v_exp_f32_e32 v170, v127
	v_add_u32_e32 v116, s58, v197
	ds_read_b128 v[112:115], v116 offset:49152
	v_add_u32_e32 v120, s58, v199
	v_add_u32_e32 v124, s58, v200
	v_add_u32_e32 v144, s58, v201
	v_exp_f32_e32 v95, v95
	v_exp_f32_e32 v160, v84
	s_waitcnt lgkmcnt(0)
	v_mfma_f32_32x32x16_bf16 v[96:111], v[112:115], v[156:159], v[64:79]
	ds_read_b128 v[112:115], v116 offset:57344
	v_add_u32_e32 v116, s58, v198
	s_waitcnt lgkmcnt(0)
	v_mfma_f32_32x32x16_bf16 v[64:79], v[112:115], v[156:159], v[64:79]
	ds_read_b128 v[112:115], v116 offset:49152
	v_exp_f32_e32 v156, v80
	v_exp_f32_e32 v157, v81
	v_exp_f32_e32 v158, v82
	v_exp_f32_e32 v159, v83
	s_waitcnt lgkmcnt(0)
	v_mfma_f32_32x32x16_bf16 v[96:111], v[112:115], v[152:155], v[96:111]
	ds_read_b128 v[112:115], v116 offset:57344
	ds_read_b128 v[116:119], v120 offset:57344
	ds_read_b128 v[120:123], v120 offset:49152
	s_waitcnt lgkmcnt(2)
	v_mfma_f32_32x32x16_bf16 v[64:79], v[112:115], v[152:155], v[64:79]
	ds_read_b128 v[112:115], v124 offset:57344
	ds_read_b128 v[124:127], v124 offset:49152
	ds_read_b128 v[132:135], v144 offset:57344
	ds_read_b128 v[144:147], v144 offset:49152
	v_add_u32_e32 v152, s58, v202
	s_waitcnt lgkmcnt(4)
	v_mfma_f32_32x32x16_bf16 v[96:111], v[120:123], v[148:151], v[96:111]
	ds_read_b128 v[120:123], v152 offset:57344
	ds_read_b128 v[152:155], v152 offset:49152
	v_add_f32_e32 v48, v48, v183
	v_add_f32_e32 v49, v49, v207
	v_cvt_pk_bf16_f32 v80, v183, v207
	v_add_f32_e32 v48, v48, v204
	v_add_f32_e32 v49, v49, v208
	v_cvt_pk_bf16_f32 v81, v204, v208
	v_add_f32_e32 v48, v48, v205
	v_add_f32_e32 v49, v49, v209
	v_cvt_pk_bf16_f32 v82, v205, v209
	v_add_f32_e32 v48, v48, v182
	v_add_f32_e32 v49, v49, v206
	v_cvt_pk_bf16_f32 v83, v182, v206
	v_add_f32_e32 v48, v48, v171
	v_add_f32_e32 v49, v49, v174
	v_cvt_pk_bf16_f32 v84, v171, v174
	v_mfma_f32_32x32x16_bf16 v[64:79], v[116:119], v[148:151], v[64:79]
	v_exp_f32_e32 v116, v85
	v_exp_f32_e32 v117, v86
	v_exp_f32_e32 v118, v87
	v_exp_f32_e32 v119, v88
	v_exp_f32_e32 v148, v89
	v_exp_f32_e32 v149, v90
	v_exp_f32_e32 v150, v91
	s_waitcnt lgkmcnt(4)
	v_mfma_f32_32x32x16_bf16 v[96:111], v[124:127], v[136:139], v[96:111]
	v_exp_f32_e32 v124, v92
	v_exp_f32_e32 v125, v93
	v_exp_f32_e32 v126, v94
	v_permlane32_swap_b32_e32 v80, v82
	v_add_f32_e32 v48, v48, v172
	v_add_f32_e32 v49, v49, v175
	v_cvt_pk_bf16_f32 v85, v172, v175
	v_add_f32_e32 v48, v48, v169
	v_add_f32_e32 v49, v49, v173
	v_cvt_pk_bf16_f32 v86, v169, v173
	v_mfma_f32_32x32x16_bf16 v[64:79], v[112:115], v[136:139], v[64:79]
	v_add_f32_e32 v48, v48, v168
	v_add_f32_e32 v49, v49, v170
	v_cvt_pk_bf16_f32 v87, v168, v170
	v_add_f32_e32 v48, v48, v156
	v_add_f32_e32 v49, v49, v157
	v_cvt_pk_bf16_f32 v88, v156, v157
	v_add_f32_e32 v48, v48, v158
	v_add_f32_e32 v49, v49, v159
	v_cvt_pk_bf16_f32 v89, v158, v159
	v_add_f32_e32 v48, v48, v160
	v_add_f32_e32 v49, v49, v116
	v_cvt_pk_bf16_f32 v90, v160, v116
	v_add_f32_e32 v48, v48, v117
	v_add_f32_e32 v49, v49, v118
	v_cvt_pk_bf16_f32 v91, v117, v118
	v_add_f32_e32 v48, v48, v119
	v_add_f32_e32 v49, v49, v148
	v_cvt_pk_bf16_f32 v92, v119, v148
	v_add_f32_e32 v48, v48, v149
	v_add_f32_e32 v49, v49, v150
	v_cvt_pk_bf16_f32 v93, v149, v150
	s_waitcnt lgkmcnt(2)
	v_mfma_f32_32x32x16_bf16 v[96:111], v[144:147], v[140:143], v[96:111]
	v_add_f32_e32 v48, v48, v124
	v_add_f32_e32 v49, v49, v125
	v_cvt_pk_bf16_f32 v94, v124, v125
	v_add_f32_e32 v48, v48, v126
	v_add_f32_e32 v49, v49, v95
	v_cvt_pk_bf16_f32 v95, v126, v95
	v_permlane32_swap_b32_e32 v81, v83
	v_permlane32_swap_b32_e32 v84, v86
	v_permlane32_swap_b32_e32 v85, v87
	v_mfma_f32_32x32x16_bf16 v[64:79], v[132:135], v[140:143], v[64:79]
	v_permlane32_swap_b32_e32 v88, v90
	v_permlane32_swap_b32_e32 v89, v91
	v_permlane32_swap_b32_e32 v92, v94
	v_permlane32_swap_b32_e32 v93, v95
	s_waitcnt lgkmcnt(0)
	v_mfma_f32_32x32x16_bf16 v[96:111], v[152:155], v[128:131], v[96:111]
	v_mfma_f32_32x32x16_bf16 v[64:79], v[120:123], v[128:131], v[64:79]
	v_add_u32_e32 v132, s40, v203
	ds_read_b64_tr_b16 v[112:113], v132 offset:0
	ds_read_b64_tr_b16 v[114:115], v132 offset:0x800
	ds_read_b64_tr_b16 v[116:117], v132 offset:0x1000
	ds_read_b64_tr_b16 v[118:119], v132 offset:0x1800
	ds_read_b64_tr_b16 v[120:121], v132 offset:0x2000
	ds_read_b64_tr_b16 v[122:123], v132 offset:0x2800
	ds_read_b64_tr_b16 v[124:125], v132 offset:0x3000
	ds_read_b64_tr_b16 v[126:127], v132 offset:0x3800
	s_waitcnt lgkmcnt(0)
	s_nop 0
	v_mfma_f32_32x32x16_bf16 v[16:31], v[80:83], v[112:115], v[16:31]
	ds_read_b64_tr_b16 v[112:113], v132 offset:0x200
	ds_read_b64_tr_b16 v[114:115], v132 offset:0xa00
	v_mfma_f32_32x32x16_bf16 v[16:31], v[84:87], v[116:119], v[16:31]
	ds_read_b64_tr_b16 v[116:117], v132 offset:0x1200
	ds_read_b64_tr_b16 v[118:119], v132 offset:0x1a00
	v_mfma_f32_32x32x16_bf16 v[16:31], v[88:91], v[120:123], v[16:31]
	ds_read_b64_tr_b16 v[120:121], v132 offset:0x2200
	ds_read_b64_tr_b16 v[122:123], v132 offset:0x2a00
	ds_read_b64_tr_b16 v[128:129], v132 offset:0x3200
	ds_read_b64_tr_b16 v[130:131], v132 offset:0x3a00
	s_waitcnt lgkmcnt(0)
	v_mfma_f32_32x32x16_bf16 v[16:31], v[92:95], v[124:127], v[16:31]
	v_mfma_f32_32x32x16_bf16 v[32:47], v[80:83], v[112:115], v[32:47]
	s_nop 3
	v_max_f32_e32 v112, v97, v97
	v_max_f32_e32 v113, v96, v96
	v_max_f32_e32 v112, v113, v112
	v_max3_f32 v112, v112, v98, v99
	v_max3_f32 v112, v112, v100, v101
	v_mfma_f32_32x32x16_bf16 v[32:47], v[84:87], v[116:119], v[32:47]
	v_max3_f32 v80, v112, v102, v103
	v_max3_f32 v80, v80, v104, v105
	v_max3_f32 v80, v80, v106, v107
	v_max3_f32 v80, v80, v108, v109
	v_max3_f32 v80, v80, v110, v111
	v_max3_f32 v80, v80, v64, v65
	v_max3_f32 v80, v80, v66, v67
	v_max3_f32 v80, v80, v68, v69
	v_max3_f32 v80, v80, v70, v71
	v_max3_f32 v80, v80, v72, v73
	v_max3_f32 v80, v80, v74, v75
	v_max3_f32 v80, v80, v76, v77
	v_max3_f32 v80, v80, v78, v79
	v_mov_b32_e32 v81, v80
	v_mfma_f32_32x32x16_bf16 v[32:47], v[88:91], v[120:123], v[32:47]
	s_nop 0
	v_permlane32_swap_b32_e32 v80, v81
	v_max_f32_e32 v81, v81, v81
	v_max_f32_e32 v80, v80, v80
	v_max_f32_e32 v80, v80, v81
	v_cmp_ge_f32_e32 vcc, s71, v80
	s_cmp_eq_u64 vcc, exec
	v_mov_b32_e32 v112, 1.0
	v_mfma_f32_32x32x16_bf16 v[32:47], v[92:95], v[128:131], v[32:47]
	s_cbranch_scc0 .LBB0_759
	v_cmp_gt_f32_e32 vcc, 1.0, v112
	s_cbranch_vccz .LBB0_704
